# previous best with the original instruction spacing restored around the matrix instructions in the compressed-attention pass-2 loops (nops where waits were removed)
# baseline (speedup 1.0000x reference)
.LBB0_1427:
	s_waitcnt vmcnt(0)
	v_mov_b64_e32 v[124:125], v[196:197]
	v_mov_b64_e32 v[126:127], v[198:199]
	v_mov_b64_e32 v[128:129], v[214:215]
	v_mov_b64_e32 v[130:131], v[216:217]
	v_mov_b64_e32 v[132:133], v[224:225]
	v_mov_b64_e32 v[134:135], v[226:227]
	v_mov_b64_e32 v[136:137], v[228:229]
	v_mov_b64_e32 v[138:139], v[230:231]
	v_mov_b64_e32 v[120:121], v[244:245]
	v_mov_b64_e32 v[122:123], v[246:247]
	v_mov_b64_e32 v[116:117], v[248:249]
	v_mov_b64_e32 v[118:119], v[250:251]
	v_mov_b64_e32 v[112:113], v[252:253]
	v_mov_b64_e32 v[114:115], v[254:255]
	v_mov_b64_e32 v[108:109], v[218:219]
	v_mov_b32_e32 v110, v220
	v_mov_b32_e32 v111, v223
	v_add_co_u32_e32 v6, vcc, s80, v164
	s_cmpk_lt_i32 s10, 0x7f
	s_nop 0
	v_addc_co_u32_e32 v7, vcc, -1, v165, vcc
	global_load_dwordx4 v[196:199], v[6:7], off offset:-3072
	global_load_dwordx4 v[214:217], v[6:7], off offset:-1024
	global_load_dwordx4 v[224:227], v[6:7], off offset:-2048
	global_load_dwordx4 v[228:231], v[6:7], off offset:0
	global_load_dwordx4 v[244:247], v[164:165], off offset:-3072
	global_load_dwordx4 v[248:251], v[164:165], off offset:-2048
	global_load_dwordx4 v[252:255], v[164:165], off offset:-1024
	global_load_dwordx2 v[218:219], v[164:165], off offset:0
	global_load_dword v220, v[164:165], off offset:8
	global_load_dword v223, v[164:165], off offset:12
	s_cselect_b64 s[8:9], -1, 0
	s_cmpk_gt_i32 s10, 0x7e
	s_mov_b64 s[6:7], -1
	s_nop 0
	v_mfma_f32_16x16x32_bf16 v[2:5], v[124:127], v[12:15], 0
	s_nop 0
	v_mfma_f32_16x16x32_bf16 v[6:9], v[128:131], v[12:15], 0
	s_nop 0
	v_mfma_f32_16x16x32_bf16 v[140:143], v[132:135], v[16:19], v[2:5]
	s_nop 0
	v_mfma_f32_16x16x32_bf16 v[144:147], v[136:139], v[16:19], v[6:9]
	s_cbranch_scc1 .LBB0_1445
	v_add_u32_e32 v149, s10, v171
	v_add_u32_e32 v4, 0x1f0, v149
	v_mov_b32_e32 v195, 0x25ffc
	v_cmp_lt_i32_e32 vcc, -1, v4
	v_mov_b32_e32 v3, 0xff800000
	v_mov_b32_e32 v2, 0xff800000
	ds_write_b32 v195, v2
	v_min_u32_e32 v2, 0x7f, v4
	v_lshl_add_u32 v2, v2, 2, s87
	v_cndmask_b32_e32 v2, v195, v2, vcc
	ds_read_b32 v2, v2
	v_add_u32_e32 v4, 0x1e0, v149
	v_cmp_lt_i32_e32 vcc, -1, v4
	v_min_u32_e32 v3, 0x7f, v4
	v_lshl_add_u32 v3, v3, 2, s87
	v_cndmask_b32_e32 v3, v195, v3, vcc
	ds_read_b32 v3, v3
	v_add_u32_e32 v6, 0x1d0, v149
	v_cmp_lt_i32_e32 vcc, -1, v6
	v_mov_b32_e32 v5, 0xff800000
	v_mov_b32_e32 v4, 0xff800000
	v_min_u32_e32 v4, 0x7f, v6
	v_lshl_add_u32 v4, v4, 2, s87
	v_cndmask_b32_e32 v4, v195, v4, vcc
	ds_read_b32 v4, v4
	v_add_u32_e32 v6, 0x1c0, v149
	v_cmp_lt_i32_e32 vcc, -1, v6
	v_min_u32_e32 v5, 0x7f, v6
	v_lshl_add_u32 v5, v5, 2, s87
	v_cndmask_b32_e32 v5, v195, v5, vcc
	ds_read_b32 v5, v5
	v_add_u32_e32 v8, 0xf0, v149
	v_cmp_lt_i32_e32 vcc, -1, v8
	v_mov_b32_e32 v7, 0xff800000
	v_mov_b32_e32 v6, 0xff800000
	v_min_u32_e32 v6, 0x7f, v8
	v_lshl_add_u32 v6, v6, 2, s87
	v_cndmask_b32_e32 v6, v195, v6, vcc
	ds_read_b32 v6, v6
	v_add_u32_e32 v8, 0xe0, v149
	v_cmp_lt_i32_e32 vcc, -1, v8
	v_min_u32_e32 v7, 0x7f, v8
	v_lshl_add_u32 v7, v7, 2, s87
	v_cndmask_b32_e32 v7, v195, v7, vcc
	ds_read_b32 v7, v7
	v_add_u32_e32 v151, 0xd0, v149
	v_cmp_lt_i32_e32 vcc, -1, v151
	v_mov_b32_e32 v9, 0xff800000
	v_mov_b32_e32 v8, 0xff800000
	v_min_u32_e32 v8, 0x7f, v151
	v_lshl_add_u32 v8, v8, 2, s87
	v_cndmask_b32_e32 v8, v195, v8, vcc
	ds_read_b32 v8, v8
	v_add_u32_e32 v149, 0xc0, v149
	v_cmp_lt_i32_e32 vcc, -1, v149
	v_min_u32_e32 v9, 0x7f, v149
	v_lshl_add_u32 v9, v9, 2, s87
	v_cndmask_b32_e32 v9, v195, v9, vcc
	ds_read_b32 v9, v9
	s_waitcnt lgkmcnt(0)
	v_add_f32_e32 v2, v140, v2
	v_mul_f32_e32 v2, 0x3fb8aa3b, v2
	v_add_f32_e32 v3, v141, v3
	v_mul_f32_e32 v3, 0x3fb8aa3b, v3
	v_add_f32_e32 v4, v142, v4
	v_mul_f32_e32 v4, 0x3fb8aa3b, v4
	v_add_f32_e32 v5, v143, v5
	v_mul_f32_e32 v5, 0x3fb8aa3b, v5
	v_add_f32_e32 v6, v144, v6
	v_mul_f32_e32 v6, 0x3fb8aa3b, v6
	v_add_f32_e32 v7, v145, v7
	v_mul_f32_e32 v7, 0x3fb8aa3b, v7
	v_add_f32_e32 v8, v146, v8
	v_mul_f32_e32 v8, 0x3fb8aa3b, v8
	v_add_f32_e32 v9, v147, v9
	v_mul_f32_e32 v9, 0x3fb8aa3b, v9
	s_mov_b64 s[6:7], 0

.LBB0_1447:
	v_sub_f32_e32 v2, v2, v166
	v_exp_f32_e32 v173, v2
	v_sub_f32_e32 v2, v3, v166
	v_exp_f32_e32 v184, v2
	v_sub_f32_e32 v2, v4, v166
	v_exp_f32_e32 v183, v2
	v_sub_f32_e32 v2, v5, v166
	v_exp_f32_e32 v182, v2
	v_sub_f32_e32 v2, v6, v166
	v_exp_f32_e32 v185, v2
	v_sub_f32_e32 v2, v7, v166
	v_exp_f32_e32 v187, v2
	v_sub_f32_e32 v2, v8, v166
	v_exp_f32_e32 v186, v2
	v_sub_f32_e32 v2, v9, v166
	v_exp_f32_e32 v149, v2
	v_cvt_pk_bf16_f32 v2, v173, v184
	v_cvt_pk_bf16_f32 v3, v183, v182
	v_cvt_pk_bf16_f32 v4, v185, v187
	v_cvt_pk_bf16_f32 v5, v186, v149
	v_cndmask_b32_e64 v6, 0, 1, s[8:9]
	s_nop 0
	v_mfma_f32_16x16x32_bf16 v[96:99], v[120:123], v[2:5], v[96:99]
	v_cmp_ne_u32_e64 s[6:7], 1, v6
	s_andn2_b64 vcc, exec, s[8:9]
	s_mov_b64 s[8:9], -1
	s_nop 0
	v_mfma_f32_16x16x32_bf16 v[104:107], v[116:119], v[2:5], v[104:107]
	s_nop 0
	v_mfma_f32_16x16x32_bf16 v[100:103], v[112:115], v[2:5], v[100:103]
	s_nop 0
	v_mfma_f32_16x16x32_bf16 v[92:95], v[108:111], v[2:5], v[92:95]
	v_mfma_f32_16x16x32_bf16 v[2:5], v[124:127], v[20:23], 0
	v_mfma_f32_16x16x32_bf16 v[140:143], v[132:135], v[24:27], v[2:5]
	v_mfma_f32_16x16x32_bf16 v[2:5], v[128:131], v[20:23], 0
	v_mfma_f32_16x16x32_bf16 v[144:147], v[136:139], v[24:27], v[2:5]
	s_cbranch_vccnz .LBB0_1465
	v_add_u32_e32 v151, s10, v171
	s_nop 4
	v_add_u32_e32 v4, 0x1f0, v151
	v_mov_b32_e32 v195, 0x25dfc
	v_cmp_lt_i32_e32 vcc, -1, v4
	v_mov_b32_e32 v3, 0xff800000
	v_mov_b32_e32 v2, 0xff800000
	ds_write_b32 v195, v2 offset:512
	v_min_u32_e32 v2, 0x7f, v4
	v_lshl_add_u32 v2, v2, 2, s87
	v_cndmask_b32_e32 v2, v195, v2, vcc
	ds_read_b32 v2, v2 offset:512
	v_add_u32_e32 v4, 0x1e0, v151
	v_cmp_lt_i32_e32 vcc, -1, v4
	v_min_u32_e32 v3, 0x7f, v4
	v_lshl_add_u32 v3, v3, 2, s87
	v_cndmask_b32_e32 v3, v195, v3, vcc
	ds_read_b32 v3, v3 offset:512
	v_add_u32_e32 v6, 0x1d0, v151
	v_cmp_lt_i32_e32 vcc, -1, v6
	v_mov_b32_e32 v5, 0xff800000
	v_mov_b32_e32 v4, 0xff800000
	v_min_u32_e32 v4, 0x7f, v6
	v_lshl_add_u32 v4, v4, 2, s87
	v_cndmask_b32_e32 v4, v195, v4, vcc
	ds_read_b32 v4, v4 offset:512
	v_add_u32_e32 v6, 0x1c0, v151
	v_cmp_lt_i32_e32 vcc, -1, v6
	v_min_u32_e32 v5, 0x7f, v6
	v_lshl_add_u32 v5, v5, 2, s87
	v_cndmask_b32_e32 v5, v195, v5, vcc
	ds_read_b32 v5, v5 offset:512
	v_add_u32_e32 v8, 0xf0, v151
	v_cmp_lt_i32_e32 vcc, -1, v8
	v_mov_b32_e32 v7, 0xff800000
	v_mov_b32_e32 v6, 0xff800000
	v_min_u32_e32 v6, 0x7f, v8
	v_lshl_add_u32 v6, v6, 2, s87
	v_cndmask_b32_e32 v6, v195, v6, vcc
	ds_read_b32 v6, v6 offset:512
	v_add_u32_e32 v8, 0xe0, v151
	v_cmp_lt_i32_e32 vcc, -1, v8
	v_min_u32_e32 v7, 0x7f, v8
	v_lshl_add_u32 v7, v7, 2, s87
	v_cndmask_b32_e32 v7, v195, v7, vcc
	ds_read_b32 v7, v7 offset:512
	v_add_u32_e32 v153, 0xd0, v151
	v_cmp_lt_i32_e32 vcc, -1, v153
	v_mov_b32_e32 v9, 0xff800000
	v_mov_b32_e32 v8, 0xff800000
	v_min_u32_e32 v8, 0x7f, v153
	v_lshl_add_u32 v8, v8, 2, s87
	v_cndmask_b32_e32 v8, v195, v8, vcc
	ds_read_b32 v8, v8 offset:512
	v_add_u32_e32 v151, 0xc0, v151
	v_cmp_lt_i32_e32 vcc, -1, v151
	v_min_u32_e32 v9, 0x7f, v151
	v_lshl_add_u32 v9, v9, 2, s87
	v_cndmask_b32_e32 v9, v195, v9, vcc
	ds_read_b32 v9, v9 offset:512
	s_waitcnt lgkmcnt(0)
	v_add_f32_e32 v2, v140, v2
	v_mul_f32_e32 v2, 0x3fb8aa3b, v2
	v_add_f32_e32 v3, v141, v3
	v_mul_f32_e32 v3, 0x3fb8aa3b, v3
	v_add_f32_e32 v4, v142, v4
	v_mul_f32_e32 v4, 0x3fb8aa3b, v4
	v_add_f32_e32 v5, v143, v5
	v_mul_f32_e32 v5, 0x3fb8aa3b, v5
	v_add_f32_e32 v6, v144, v6
	v_mul_f32_e32 v6, 0x3fb8aa3b, v6
	v_add_f32_e32 v7, v145, v7
	v_mul_f32_e32 v7, 0x3fb8aa3b, v7
	v_add_f32_e32 v8, v146, v8
	v_mul_f32_e32 v8, 0x3fb8aa3b, v8
	v_add_f32_e32 v9, v147, v9
	v_mul_f32_e32 v9, 0x3fb8aa3b, v9
	s_mov_b64 s[8:9], 0

.LBB0_1927:
	s_waitcnt vmcnt(0)
	v_mov_b64_e32 v[124:125], v[196:197]
	v_mov_b64_e32 v[126:127], v[198:199]
	v_mov_b64_e32 v[128:129], v[232:233]
	v_mov_b64_e32 v[130:131], v[234:235]
	v_mov_b64_e32 v[132:133], v[244:245]
	v_mov_b64_e32 v[134:135], v[246:247]
	v_mov_b64_e32 v[136:137], v[248:249]
	v_mov_b64_e32 v[138:139], v[250:251]
	v_mov_b64_e32 v[120:121], v[252:253]
	v_mov_b64_e32 v[122:123], v[254:255]
	v_mov_b64_e32 v[116:117], v[228:229]
	v_mov_b64_e32 v[118:119], v[236:237]
	v_mov_b32_e32 v112, v195
	v_mov_b32_e32 v113, v200
	v_mov_b32_e32 v114, v203
	v_mov_b32_e32 v115, v221
	v_mov_b32_e32 v108, v222
	v_mov_b32_e32 v109, v231
	v_mov_b32_e32 v110, v239
	v_mov_b32_e32 v111, v240
	v_add_co_u32_e32 v6, vcc, s80, v164
	s_cmpk_lt_i32 s23, 0x7f
	s_nop 0
	v_addc_co_u32_e32 v7, vcc, -1, v165, vcc
	global_load_dwordx4 v[196:199], v[6:7], off offset:-3072
	global_load_dwordx4 v[232:235], v[6:7], off offset:-1024
	global_load_dwordx4 v[244:247], v[6:7], off offset:-2048
	global_load_dwordx4 v[248:251], v[6:7], off offset:0
	global_load_dwordx4 v[252:255], v[164:165], off offset:-3072
	global_load_dwordx2 v[228:229], v[164:165], off offset:-2048
	global_load_dwordx2 v[236:237], v[164:165], off offset:-2040
	global_load_dword v195, v[164:165], off offset:-1024
	global_load_dword v200, v[164:165], off offset:-1020
	global_load_dword v203, v[164:165], off offset:-1016
	global_load_dword v221, v[164:165], off offset:-1012
	global_load_dword v222, v[164:165], off offset:0
	global_load_dword v231, v[164:165], off offset:4
	global_load_dword v239, v[164:165], off offset:8
	global_load_dword v240, v[164:165], off offset:12
	s_cselect_b64 s[14:15], -1, 0
	s_cmpk_gt_i32 s23, 0x7e
	s_mov_b64 s[12:13], -1
	s_nop 0
	v_mfma_f32_16x16x32_bf16 v[2:5], v[124:127], v[12:15], 0
	s_nop 0
	v_mfma_f32_16x16x32_bf16 v[6:9], v[128:131], v[12:15], 0
	s_nop 0
	v_mfma_f32_16x16x32_bf16 v[140:143], v[132:135], v[16:19], v[2:5]
	s_nop 0
	v_mfma_f32_16x16x32_bf16 v[144:147], v[136:139], v[16:19], v[6:9]
	s_cbranch_scc1 .LBB0_1945
	v_add_u32_e32 v149, s23, v171
	v_add_u32_e32 v4, 0x1f0, v149
	v_cmp_lt_i32_e32 vcc, -1, v4
	v_mov_b32_e32 v3, 0xff800000
	v_mov_b32_e32 v2, 0xff800000
	s_and_saveexec_b64 s[12:13], vcc
	s_cbranch_execz .LBB0_1930
	v_min_u32_e32 v2, 0x7f, v4
	v_lshl_add_u32 v2, v2, 2, s87
	ds_read_b32 v2, v2
	s_waitcnt lgkmcnt(0)
	v_add_f32_e32 v2, v140, v2
	v_mul_f32_e32 v2, 0x3fb8aa3b, v2

.LBB0_1947:
	v_sub_f32_e32 v2, v2, v166
	v_exp_f32_e32 v173, v2
	v_sub_f32_e32 v2, v3, v166
	v_exp_f32_e32 v184, v2
	v_sub_f32_e32 v2, v4, v166
	v_exp_f32_e32 v183, v2
	v_sub_f32_e32 v2, v5, v166
	v_exp_f32_e32 v182, v2
	v_sub_f32_e32 v2, v6, v166
	v_exp_f32_e32 v185, v2
	v_sub_f32_e32 v2, v7, v166
	v_exp_f32_e32 v187, v2
	v_sub_f32_e32 v2, v8, v166
	v_exp_f32_e32 v186, v2
	v_sub_f32_e32 v2, v9, v166
	v_exp_f32_e32 v149, v2
	v_cvt_pk_bf16_f32 v2, v173, v184
	v_cvt_pk_bf16_f32 v3, v183, v182
	v_cvt_pk_bf16_f32 v4, v185, v187
	v_cvt_pk_bf16_f32 v5, v186, v149
	v_cndmask_b32_e64 v6, 0, 1, s[14:15]
	s_nop 0
	v_mfma_f32_16x16x32_bf16 v[96:99], v[120:123], v[2:5], v[96:99]
	v_cmp_ne_u32_e64 s[12:13], 1, v6
	s_andn2_b64 vcc, exec, s[14:15]
	s_mov_b64 s[14:15], -1
	s_nop 0
	v_mfma_f32_16x16x32_bf16 v[104:107], v[116:119], v[2:5], v[104:107]
	s_nop 0
	v_mfma_f32_16x16x32_bf16 v[100:103], v[112:115], v[2:5], v[100:103]
	s_nop 0
	v_mfma_f32_16x16x32_bf16 v[92:95], v[108:111], v[2:5], v[92:95]
	v_mfma_f32_16x16x32_bf16 v[2:5], v[124:127], v[20:23], 0
	v_mfma_f32_16x16x32_bf16 v[140:143], v[132:135], v[24:27], v[2:5]
	v_mfma_f32_16x16x32_bf16 v[2:5], v[128:131], v[20:23], 0
	v_mfma_f32_16x16x32_bf16 v[144:147], v[136:139], v[24:27], v[2:5]
	s_cbranch_vccnz .LBB0_1965
	v_add_u32_e32 v151, s23, v171
	s_nop 4
	v_add_u32_e32 v4, 0x1f0, v151
	v_cmp_lt_i32_e32 vcc, -1, v4
	v_mov_b32_e32 v3, 0xff800000
	v_mov_b32_e32 v2, 0xff800000
	s_and_saveexec_b64 s[14:15], vcc
	s_cbranch_execz .LBB0_1950
	v_min_u32_e32 v2, 0x7f, v4
	v_lshl_add_u32 v2, v2, 2, s87
	ds_read_b32 v2, v2 offset:512
	s_waitcnt lgkmcnt(0)
	v_add_f32_e32 v2, v140, v2
	v_mul_f32_e32 v2, 0x3fb8aa3b, v2
